# P1/P4 GEMM tile loops: first body of each tile peeled, first MFMA per accumulator takes C=0, 128 zeroing v_mov per tile head removed
# speedup vs baseline: 1.0059x; 1.0016x over previous
; #define PG8_STAGE(bufoff, gbase, voff) do { _Pragma("unroll") for (int _i = 0; _i < 2; ++_i) \
;         __builtin_amdgcn_global_load_lds((const unsigned*)((const char*)(gbase) + (voff)[_i]), (LAS unsigned*)(lds + (bufoff) + ldsw + _i * 8192), 16, 0, 0); } while (0)
; #define PG8_LDA(dst, b, h) do { _Pragma("unroll") for (int m = 0; m < 4; ++m) _Pragma("unroll") for (int k = 0; k < 2; ++k) dst[m][k] = *(const LAS bf16x8*)(lds + PG8_SA(b, h) + aoff + m * 2048 + k * 1024); } while (0)
; #define PG8_LDB(dst, b, h) do { _Pragma("unroll") for (int n = 0; n < 2; ++n) _Pragma("unroll") for (int k = 0; k < 2; ++k) dst[n][k] = *(const LAS bf16x8*)(lds + PG8_SB(b, h) + boff + n * 2048 + k * 1024); } while (0)
; #define PG8_MMA(ai, bj, At, Bt) do { __builtin_amdgcn_s_setprio(1); _Pragma("unroll") for (int m = 0; m < 4; ++m) _Pragma("unroll") for (int n = 0; n < 2; ++n) _Pragma("unroll") for (int k = 0; k < 2; ++k) \
;         acc[ai][bj][m][n] = __builtin_amdgcn_mfma_f32_16x16x32_bf16(Bt[n][k], At[m][k], acc[ai][bj][m][n], 0, 0, 0); __builtin_amdgcn_s_setprio(0); } while (0)
; #define PG8_WAIT_L(n) asm volatile("s_waitcnt lgkmcnt(" #n ")" ::: "memory")
; template <class Epi, bool AFTER = false>
; __device__ __forceinline__ void gemm_phase(LAS unsigned char* lds, const Gemm g, const StaticOrder& S, const Epi& E) {
;     ...
;         const bool has_next = S.next(ui + 1, nxt);
;         const char* nA = has_next ? (const char*)g.A + (size_t)nxt.pm * tstep : cA; const char* nB = has_next ? (const char*)g.Bt + (size_t)nxt.pn * tstep : cB;
;         for (int t = 0; t < nt; t += 2) {
;             const bool last = (t == nt - 2);
;             const char* a1 = cA + (size_t)(t + 1) * kstep;
;             const char* a2 = last ? nA : cA + (size_t)(t + 2) * kstep; const char* b2 = last ? nB : cB + (size_t)(t + 2) * kstep;
;             const char* a3 = a2 + kstep; const char* b3 = b2 + kstep;
;             PG8_LDB(B0, 0, 0); PG8_SCHED; PG8_LDA(At, 0, 0); PG8_STAGE(PG8_SA(1, 1), a1 + hstep, voffA);
;             PG8_WAIT_L(8); PG8_BAR; PG8_WAIT_L(0); PG8_MMA(0, 0, At, B0); PG8_BAR; PG8_SCHED;
;             PG8_LDB(B1, 0, 1); PG8_STAGE(PG8_SB(0, 0), b2, voffB);
;             PG8_BAR; PG8_WAIT_L(0); PG8_MMA(0, 1, At, B1); PG8_BAR;
;             PG8_LDA(At, 0, 1); PG8_STAGE(PG8_SA(0, 0), a2, voffA);
;             PG8_BAR; PG8_WAIT_L(0); PG8_MMA(1, 0, At, B0); PG8_BAR; PG8_SCHED;
.LBB0_117:
	s_ashr_i32 s11, s10, 31
	v_cmp_lt_i64_e32 vcc, s[12:13], v[140:141]
	s_lshl_b64 s[12:13], s[10:11], 19
	s_add_u32 s12, s74, s12
	s_addc_u32 s13, s75, s13
	s_and_b64 s[14:15], vcc, exec
	s_cselect_b32 s11, s13, s17
	s_cselect_b32 s39, s12, s16
	s_ashr_i32 s9, s8, 31
	s_lshl_b64 s[14:15], s[8:9], 19
	s_add_u32 s14, s88, s14
	s_addc_u32 s15, s89, s15
	s_and_b64 s[20:21], vcc, exec
	s_cselect_b32 s9, s15, s19
	s_cselect_b32 s40, s14, s18
	s_add_u32 s16, s16, 0x40080
	s_addc_u32 s17, s17, 0
	s_add_u32 s41, s18, 0x100
	s_addc_u32 s42, s19, 0
	s_mov_b32 s43, -2
	ds_read_b128 v[150:153], v147
	ds_read_b128 v[154:157], v147 offset:1024
	ds_read_b128 v[158:161], v147 offset:2048
	ds_read_b128 v[162:165], v147 offset:3072
	s_add_u32 s18, s16, 0xfffc0080
	s_addc_u32 s19, s17, -1
	s_cmp_eq_u32 s43, 12
	s_cselect_b32 s21, s11, s19
	s_cselect_b32 s20, s39, s18
	s_cselect_b32 s19, s9, s42
	s_cselect_b32 s18, s40, s41
	v_lshl_add_u64 v[200:201], s[16:17], 0, v[136:137]
	s_add_i32 m0, s7, 0xc000
	ds_read_b128 v[166:169], v148
	ds_read_b128 v[170:173], v148 offset:1024
	ds_read_b128 v[174:177], v148 offset:2048
	ds_read_b128 v[178:181], v148 offset:3072
	ds_read_b128 v[182:185], v148 offset:4096
	ds_read_b128 v[186:189], v148 offset:5120
	ds_read_b128 v[192:195], v148 offset:6144
	ds_read_b128 v[196:199], v148 offset:7168
	global_load_lds_dwordx4 v[200:201], off
	v_lshl_add_u64 v[200:201], s[16:17], 0, v[138:139]
	s_add_i32 m0, s7, 0xe000
	s_nop 0
	global_load_lds_dwordx4 v[200:201], off
	s_waitcnt lgkmcnt(8)
	s_barrier
	s_waitcnt lgkmcnt(0)
	s_setprio 1
	s_waitcnt lgkmcnt(0)
	v_mfma_f32_16x16x32_bf16 v[124:127], v[150:153], v[166:169], 0
	v_mfma_f32_16x16x32_bf16 v[120:123], v[158:161], v[166:169], 0
	v_mfma_f32_16x16x32_bf16 v[116:119], v[150:153], v[174:177], 0
	v_mfma_f32_16x16x32_bf16 v[112:115], v[158:161], v[174:177], 0
	v_mfma_f32_16x16x32_bf16 v[100:103], v[150:153], v[182:185], 0
	v_mfma_f32_16x16x32_bf16 v[96:99], v[158:161], v[182:185], 0
	v_mfma_f32_16x16x32_bf16 v[84:87], v[150:153], v[192:195], 0
	v_mfma_f32_16x16x32_bf16 v[80:83], v[158:161], v[192:195], 0
	v_mfma_f32_16x16x32_bf16 v[124:127], v[154:157], v[170:173], v[124:127]
	v_mfma_f32_16x16x32_bf16 v[120:123], v[162:165], v[170:173], v[120:123]
	v_mfma_f32_16x16x32_bf16 v[116:119], v[154:157], v[178:181], v[116:119]
	v_mfma_f32_16x16x32_bf16 v[112:115], v[162:165], v[178:181], v[112:115]
	v_mfma_f32_16x16x32_bf16 v[100:103], v[154:157], v[186:189], v[100:103]
	v_mfma_f32_16x16x32_bf16 v[96:99], v[162:165], v[186:189], v[96:99]
	v_mfma_f32_16x16x32_bf16 v[84:87], v[154:157], v[196:199], v[84:87]
	v_mfma_f32_16x16x32_bf16 v[80:83], v[162:165], v[196:199], v[80:83]
	s_setprio 0
	s_barrier
	s_add_i32 s44, s35, s23
	v_lshl_add_u64 v[218:219], s[18:19], 0, v[130:131]
	s_mov_b32 m0, s44
	ds_read_b128 v[200:203], v149
	ds_read_b128 v[204:207], v149 offset:1024
	ds_read_b128 v[208:211], v149 offset:2048
	ds_read_b128 v[214:217], v149 offset:3072
	global_load_lds_dwordx4 v[218:219], off
	v_lshl_add_u64 v[220:221], s[18:19], 0, v[134:135]
	s_add_i32 m0, s44, 0x2000
	s_nop 0
	global_load_lds_dwordx4 v[220:221], off
	s_barrier
	s_waitcnt lgkmcnt(0)
	s_setprio 1
	s_waitcnt lgkmcnt(0)
	v_mfma_f32_16x16x32_bf16 v[108:111], v[200:203], v[166:169], 0
	v_mfma_f32_16x16x32_bf16 v[104:107], v[208:211], v[166:169], 0
	v_mfma_f32_16x16x32_bf16 v[92:95], v[200:203], v[174:177], 0
	v_mfma_f32_16x16x32_bf16 v[88:91], v[208:211], v[174:177], 0
	v_mfma_f32_16x16x32_bf16 v[76:79], v[200:203], v[182:185], 0
	v_mfma_f32_16x16x32_bf16 v[72:75], v[208:211], v[182:185], 0
	v_mfma_f32_16x16x32_bf16 v[68:71], v[200:203], v[192:195], 0
	v_mfma_f32_16x16x32_bf16 v[64:67], v[208:211], v[192:195], 0
	v_mfma_f32_16x16x32_bf16 v[108:111], v[204:207], v[170:173], v[108:111]
	v_mfma_f32_16x16x32_bf16 v[104:107], v[214:217], v[170:173], v[104:107]
	v_mfma_f32_16x16x32_bf16 v[92:95], v[204:207], v[178:181], v[92:95]
	v_mfma_f32_16x16x32_bf16 v[88:91], v[214:217], v[178:181], v[88:91]
	v_mfma_f32_16x16x32_bf16 v[76:79], v[204:207], v[186:189], v[76:79]
	v_mfma_f32_16x16x32_bf16 v[72:75], v[214:217], v[186:189], v[72:75]
	v_mfma_f32_16x16x32_bf16 v[68:71], v[204:207], v[196:199], v[68:71]
	v_mfma_f32_16x16x32_bf16 v[64:67], v[214:217], v[196:199], v[64:67]
	s_setprio 0
	s_mov_b32 m0, s7
	v_lshl_add_u64 v[222:223], s[20:21], 0, v[128:129]
	s_barrier
	ds_read_b128 v[166:169], v148 offset:16384
	ds_read_b128 v[170:173], v148 offset:17408
	ds_read_b128 v[174:177], v148 offset:18432
	ds_read_b128 v[178:181], v148 offset:19456
	ds_read_b128 v[182:185], v148 offset:20480
	ds_read_b128 v[186:189], v148 offset:21504
	ds_read_b128 v[192:195], v148 offset:22528
	ds_read_b128 v[196:199], v148 offset:23552
	global_load_lds_dwordx4 v[222:223], off
	v_lshl_add_u64 v[224:225], s[20:21], 0, v[132:133]
	s_mov_b32 m0, s26
	s_nop 0
	global_load_lds_dwordx4 v[224:225], off
	s_barrier
	s_waitcnt lgkmcnt(0)
	s_setprio 1
	s_waitcnt lgkmcnt(0)
	v_mfma_f32_16x16x32_bf16 v[60:63], v[150:153], v[166:169], 0
	v_mfma_f32_16x16x32_bf16 v[56:59], v[158:161], v[166:169], 0
	v_mfma_f32_16x16x32_bf16 v[52:55], v[150:153], v[174:177], 0
	v_mfma_f32_16x16x32_bf16 v[48:51], v[158:161], v[174:177], 0
	v_mfma_f32_16x16x32_bf16 v[36:39], v[150:153], v[182:185], 0
	v_mfma_f32_16x16x32_bf16 v[32:35], v[158:161], v[182:185], 0
	v_mfma_f32_16x16x32_bf16 v[20:23], v[150:153], v[192:195], 0
	v_mfma_f32_16x16x32_bf16 v[16:19], v[158:161], v[192:195], 0
	v_mfma_f32_16x16x32_bf16 v[60:63], v[154:157], v[170:173], v[60:63]
	v_mfma_f32_16x16x32_bf16 v[56:59], v[162:165], v[170:173], v[56:59]
	v_mfma_f32_16x16x32_bf16 v[52:55], v[154:157], v[178:181], v[52:55]
	v_mfma_f32_16x16x32_bf16 v[48:51], v[162:165], v[178:181], v[48:51]
	v_mfma_f32_16x16x32_bf16 v[36:39], v[154:157], v[186:189], v[36:39]
	v_mfma_f32_16x16x32_bf16 v[32:35], v[162:165], v[186:189], v[32:35]
	v_mfma_f32_16x16x32_bf16 v[20:23], v[154:157], v[196:199], v[20:23]
	v_mfma_f32_16x16x32_bf16 v[16:19], v[162:165], v[196:199], v[16:19]
	s_setprio 0
	s_barrier
; #define PG8_STAGE(bufoff, gbase, voff) do { _Pragma("unroll") for (int _i = 0; _i < 2; ++_i) \
;         __builtin_amdgcn_global_load_lds((const unsigned*)((const char*)(gbase) + (voff)[_i]), (LAS unsigned*)(lds + (bufoff) + ldsw + _i * 8192), 16, 0, 0); } while (0)
; #define PG8_LDA(dst, b, h) do { _Pragma("unroll") for (int m = 0; m < 4; ++m) _Pragma("unroll") for (int k = 0; k < 2; ++k) dst[m][k] = *(const LAS bf16x8*)(lds + PG8_SA(b, h) + aoff + m * 2048 + k * 1024); } while (0)
; #define PG8_LDB(dst, b, h) do { _Pragma("unroll") for (int n = 0; n < 2; ++n) _Pragma("unroll") for (int k = 0; k < 2; ++k) dst[n][k] = *(const LAS bf16x8*)(lds + PG8_SB(b, h) + boff + n * 2048 + k * 1024); } while (0)
; #define PG8_MMA(ai, bj, At, Bt) do { __builtin_amdgcn_s_setprio(1); _Pragma("unroll") for (int m = 0; m < 4; ++m) _Pragma("unroll") for (int n = 0; n < 2; ++n) _Pragma("unroll") for (int k = 0; k < 2; ++k) \
;         acc[ai][bj][m][n] = __builtin_amdgcn_mfma_f32_16x16x32_bf16(Bt[n][k], At[m][k], acc[ai][bj][m][n], 0, 0, 0); __builtin_amdgcn_s_setprio(0); } while (0)
; #define PG8_WAIT_V(n) asm volatile("s_waitcnt vmcnt(" #n ")" ::: "memory")
; #define PG8_WAIT_L(n) asm volatile("s_waitcnt lgkmcnt(" #n ")" ::: "memory")
; #define PG8_BAR __builtin_amdgcn_s_barrier()
; #define PG8_SCHED __builtin_amdgcn_sched_barrier(0)
; #define PG8_LDA(dst, b, h) do { _Pragma("unroll") for (int m = 0; m < 4; ++m) _Pragma("unroll") for (int k = 0; k < 2; ++k) dst[m][k] = *(const LAS bf16x8*)(lds + PG8_SA(b, h) + aoff + m * 2048 + k * 1024); } while (0)
; #define PG8_LDB(dst, b, h) do { _Pragma("unroll") for (int n = 0; n < 2; ++n) _Pragma("unroll") for (int k = 0; k < 2; ++k) dst[n][k] = *(const LAS bf16x8*)(lds + PG8_SB(b, h) + boff + n * 2048 + k * 1024); } while (0)
; #define PG8_BAR __builtin_amdgcn_s_barrier()
; template <class Epi, bool AFTER = false>
; __device__ __forceinline__ void gemm_phase(LAS unsigned char* lds, const Gemm g, const StaticOrder& S, const Epi& E) {
;     ...
;             PG8_STAGE(PG8_SB(0, 1), b2 + hstep, voffB);
;             PG8_WAIT_V(6); PG8_BAR; PG8_MMA(1, 1, At, B1); PG8_BAR;
;             PG8_LDB(B0, 1, 0); PG8_SCHED; PG8_LDA(At, 1, 0); PG8_STAGE(PG8_SA(0, 1), a2 + hstep, voffA);
;             PG8_WAIT_L(8); PG8_BAR; PG8_WAIT_L(0); PG8_MMA(0, 0, At, B0); PG8_BAR; PG8_SCHED;
;             PG8_LDB(B1, 1, 1); PG8_STAGE(PG8_SB(1, 0), b3, voffB);
	s_add_u32 s44, s18, 0x40000
	s_addc_u32 s45, s19, 0
	s_add_i32 s46, s36, s23
	v_lshl_add_u64 v[150:151], s[44:45], 0, v[130:131]
	s_mov_b32 m0, s46
	s_nop 0
	global_load_lds_dwordx4 v[150:151], off
	v_lshl_add_u64 v[150:151], s[44:45], 0, v[134:135]
	s_add_i32 m0, s46, 0x2000
	s_nop 0
	global_load_lds_dwordx4 v[150:151], off
	s_waitcnt vmcnt(6)
	s_barrier
	s_setprio 1
	v_mfma_f32_16x16x32_bf16 v[44:47], v[200:203], v[166:169], 0
	v_mfma_f32_16x16x32_bf16 v[40:43], v[208:211], v[166:169], 0
	v_mfma_f32_16x16x32_bf16 v[28:31], v[200:203], v[174:177], 0
	v_mfma_f32_16x16x32_bf16 v[24:27], v[208:211], v[174:177], 0
	v_mfma_f32_16x16x32_bf16 v[12:15], v[200:203], v[182:185], 0
	v_mfma_f32_16x16x32_bf16 v[8:11], v[208:211], v[182:185], 0
	v_mfma_f32_16x16x32_bf16 v[4:7], v[200:203], v[192:195], 0
	v_mfma_f32_16x16x32_bf16 v[0:3], v[208:211], v[192:195], 0
	v_mfma_f32_16x16x32_bf16 v[44:47], v[204:207], v[170:173], v[44:47]
	v_mfma_f32_16x16x32_bf16 v[40:43], v[214:217], v[170:173], v[40:43]
	v_mfma_f32_16x16x32_bf16 v[28:31], v[204:207], v[178:181], v[28:31]
	v_mfma_f32_16x16x32_bf16 v[24:27], v[214:217], v[178:181], v[24:27]
	v_mfma_f32_16x16x32_bf16 v[12:15], v[204:207], v[186:189], v[12:15]
	v_mfma_f32_16x16x32_bf16 v[8:11], v[214:217], v[186:189], v[8:11]
	v_mfma_f32_16x16x32_bf16 v[4:7], v[204:207], v[196:199], v[4:7]
	v_mfma_f32_16x16x32_bf16 v[0:3], v[214:217], v[196:199], v[0:3]
	s_setprio 0
	s_add_i32 s44, 0, 0x18000
	v_add_u32_e32 v162, s44, v145
	s_barrier
	ds_read_b128 v[150:153], v162
	ds_read_b128 v[154:157], v162 offset:1024
	ds_read_b128 v[158:161], v162 offset:2048
	ds_read_b128 v[162:165], v162 offset:3072
	s_add_u32 s20, s20, 0x40000
	s_addc_u32 s21, s21, 0
	s_mov_b32 m0, s27
	v_lshl_add_u64 v[200:201], s[20:21], 0, v[128:129]
	ds_read_b128 v[166:169], v148 offset:32768
	ds_read_b128 v[170:173], v148 offset:33792
	ds_read_b128 v[174:177], v148 offset:34816
	ds_read_b128 v[178:181], v148 offset:35840
	ds_read_b128 v[182:185], v148 offset:36864
	ds_read_b128 v[186:189], v148 offset:37888
	ds_read_b128 v[192:195], v148 offset:38912
	ds_read_b128 v[196:199], v148 offset:39936
	global_load_lds_dwordx4 v[200:201], off
	v_lshl_add_u64 v[200:201], s[20:21], 0, v[132:133]
	s_mov_b32 m0, s28
	s_nop 0
	global_load_lds_dwordx4 v[200:201], off
	s_waitcnt lgkmcnt(8)
	s_barrier
	s_waitcnt lgkmcnt(0)
	s_setprio 1
	s_waitcnt lgkmcnt(0)
	v_mfma_f32_16x16x32_bf16 v[124:127], v[150:153], v[166:169], v[124:127]
	v_mfma_f32_16x16x32_bf16 v[120:123], v[158:161], v[166:169], v[120:123]
	v_mfma_f32_16x16x32_bf16 v[116:119], v[150:153], v[174:177], v[116:119]
	v_mfma_f32_16x16x32_bf16 v[112:115], v[158:161], v[174:177], v[112:115]
	v_mfma_f32_16x16x32_bf16 v[100:103], v[150:153], v[182:185], v[100:103]
	v_mfma_f32_16x16x32_bf16 v[96:99], v[158:161], v[182:185], v[96:99]
	v_mfma_f32_16x16x32_bf16 v[84:87], v[150:153], v[192:195], v[84:87]
	v_mfma_f32_16x16x32_bf16 v[80:83], v[158:161], v[192:195], v[80:83]
	v_mfma_f32_16x16x32_bf16 v[124:127], v[154:157], v[170:173], v[124:127]
	v_mfma_f32_16x16x32_bf16 v[120:123], v[162:165], v[170:173], v[120:123]
	v_mfma_f32_16x16x32_bf16 v[116:119], v[154:157], v[178:181], v[116:119]
	v_mfma_f32_16x16x32_bf16 v[112:115], v[162:165], v[178:181], v[112:115]
	v_mfma_f32_16x16x32_bf16 v[100:103], v[154:157], v[186:189], v[100:103]
	v_mfma_f32_16x16x32_bf16 v[96:99], v[162:165], v[186:189], v[96:99]
	v_mfma_f32_16x16x32_bf16 v[84:87], v[154:157], v[196:199], v[84:87]
	v_mfma_f32_16x16x32_bf16 v[80:83], v[162:165], v[196:199], v[80:83]
	s_setprio 0
	s_barrier
	s_add_i32 s20, 0, 0x1c000
	s_add_i32 s21, s44, s23
	v_add_u32_e32 v191, s20, v145
	v_lshl_add_u64 v[218:219], v[218:219], 0, s[4:5]
	s_mov_b32 m0, s21
	ds_read_b128 v[200:203], v191
	ds_read_b128 v[204:207], v191 offset:1024
	ds_read_b128 v[208:211], v191 offset:2048
	ds_read_b128 v[214:217], v191 offset:3072
	global_load_lds_dwordx4 v[218:219], off
	v_lshl_add_u64 v[218:219], v[220:221], 0, s[4:5]
	s_add_i32 m0, s21, 0x2000
	s_nop 0
	global_load_lds_dwordx4 v[218:219], off
	s_barrier
; #define PG8_STAGE(bufoff, gbase, voff) do { _Pragma("unroll") for (int _i = 0; _i < 2; ++_i) \
;         __builtin_amdgcn_global_load_lds((const unsigned*)((const char*)(gbase) + (voff)[_i]), (LAS unsigned*)(lds + (bufoff) + ldsw + _i * 8192), 16, 0, 0); } while (0)
; #define PG8_LDA(dst, b, h) do { _Pragma("unroll") for (int m = 0; m < 4; ++m) _Pragma("unroll") for (int k = 0; k < 2; ++k) dst[m][k] = *(const LAS bf16x8*)(lds + PG8_SA(b, h) + aoff + m * 2048 + k * 1024); } while (0)
; #define PG8_MMA(ai, bj, At, Bt) do { __builtin_amdgcn_s_setprio(1); _Pragma("unroll") for (int m = 0; m < 4; ++m) _Pragma("unroll") for (int n = 0; n < 2; ++n) _Pragma("unroll") for (int k = 0; k < 2; ++k) \
;         acc[ai][bj][m][n] = __builtin_amdgcn_mfma_f32_16x16x32_bf16(Bt[n][k], At[m][k], acc[ai][bj][m][n], 0, 0, 0); __builtin_amdgcn_s_setprio(0); } while (0)
; #define PG8_WAIT_V(n) asm volatile("s_waitcnt vmcnt(" #n ")" ::: "memory")
; #define PG8_WAIT_L(n) asm volatile("s_waitcnt lgkmcnt(" #n ")" ::: "memory")
; #define PG8_BAR __builtin_amdgcn_s_barrier()
; #define PG8_SCHED __builtin_amdgcn_sched_barrier(0)
; #define PG8_LDA(dst, b, h) do { _Pragma("unroll") for (int m = 0; m < 4; ++m) _Pragma("unroll") for (int k = 0; k < 2; ++k) dst[m][k] = *(const LAS bf16x8*)(lds + PG8_SA(b, h) + aoff + m * 2048 + k * 1024); } while (0)
; #define PG8_MMA(ai, bj, At, Bt) do { __builtin_amdgcn_s_setprio(1); _Pragma("unroll") for (int m = 0; m < 4; ++m) _Pragma("unroll") for (int n = 0; n < 2; ++n) _Pragma("unroll") for (int k = 0; k < 2; ++k) \
;         acc[ai][bj][m][n] = __builtin_amdgcn_mfma_f32_16x16x32_bf16(Bt[n][k], At[m][k], acc[ai][bj][m][n], 0, 0, 0); __builtin_amdgcn_s_setprio(0); } while (0)
; #define PG8_WAIT_V(n) asm volatile("s_waitcnt vmcnt(" #n ")" ::: "memory")
; #define PG8_WAIT_L(n) asm volatile("s_waitcnt lgkmcnt(" #n ")" ::: "memory")
; template <class Epi, bool AFTER = false>
; __device__ __forceinline__ void gemm_phase(LAS unsigned char* lds, const Gemm g, const StaticOrder& S, const Epi& E) {
;     ...
;             PG8_BAR; PG8_WAIT_L(0); PG8_MMA(0, 1, At, B1); PG8_BAR;
;             PG8_LDA(At, 1, 1); PG8_STAGE(PG8_SA(1, 0), a3, voffA);
;             PG8_BAR; PG8_WAIT_L(0); PG8_MMA(1, 0, At, B0); PG8_BAR; PG8_SCHED;
;             PG8_STAGE(PG8_SB(1, 1), b3 + hstep, voffB);
;             PG8_WAIT_V(6); PG8_BAR; PG8_MMA(1, 1, At, B1); PG8_BAR;
;         }
	s_waitcnt lgkmcnt(0)
	s_setprio 1
	s_waitcnt lgkmcnt(0)
	v_mfma_f32_16x16x32_bf16 v[108:111], v[200:203], v[166:169], v[108:111]
	v_mfma_f32_16x16x32_bf16 v[104:107], v[208:211], v[166:169], v[104:107]
	v_mfma_f32_16x16x32_bf16 v[92:95], v[200:203], v[174:177], v[92:95]
	v_mfma_f32_16x16x32_bf16 v[88:91], v[208:211], v[174:177], v[88:91]
	v_mfma_f32_16x16x32_bf16 v[76:79], v[200:203], v[182:185], v[76:79]
	v_mfma_f32_16x16x32_bf16 v[72:75], v[208:211], v[182:185], v[72:75]
	v_mfma_f32_16x16x32_bf16 v[68:71], v[200:203], v[192:195], v[68:71]
	v_mfma_f32_16x16x32_bf16 v[64:67], v[208:211], v[192:195], v[64:67]
	v_mfma_f32_16x16x32_bf16 v[108:111], v[204:207], v[170:173], v[108:111]
	v_mfma_f32_16x16x32_bf16 v[104:107], v[214:217], v[170:173], v[104:107]
	v_mfma_f32_16x16x32_bf16 v[92:95], v[204:207], v[178:181], v[92:95]
	v_mfma_f32_16x16x32_bf16 v[88:91], v[214:217], v[178:181], v[88:91]
	v_mfma_f32_16x16x32_bf16 v[76:79], v[204:207], v[186:189], v[76:79]
	v_mfma_f32_16x16x32_bf16 v[72:75], v[214:217], v[186:189], v[72:75]
	v_mfma_f32_16x16x32_bf16 v[68:71], v[204:207], v[196:199], v[68:71]
	v_mfma_f32_16x16x32_bf16 v[64:67], v[214:217], v[196:199], v[64:67]
	s_setprio 0
	s_mov_b32 m0, s31
	v_lshl_add_u64 v[218:219], v[222:223], 0, s[4:5]
	s_barrier
	ds_read_b128 v[166:169], v148 offset:49152
	ds_read_b128 v[170:173], v148 offset:50176
	ds_read_b128 v[174:177], v148 offset:51200
	ds_read_b128 v[178:181], v148 offset:52224
	ds_read_b128 v[182:185], v148 offset:53248
	ds_read_b128 v[186:189], v148 offset:54272
	ds_read_b128 v[192:195], v148 offset:55296
	ds_read_b128 v[196:199], v148 offset:56320
	global_load_lds_dwordx4 v[218:219], off
	v_lshl_add_u64 v[218:219], v[224:225], 0, s[4:5]
	s_mov_b32 m0, s33
	s_nop 0
	global_load_lds_dwordx4 v[218:219], off
	s_barrier
	s_waitcnt lgkmcnt(0)
	s_setprio 1
	s_waitcnt lgkmcnt(0)
	v_mfma_f32_16x16x32_bf16 v[60:63], v[150:153], v[166:169], v[60:63]
	v_mfma_f32_16x16x32_bf16 v[56:59], v[158:161], v[166:169], v[56:59]
	v_mfma_f32_16x16x32_bf16 v[52:55], v[150:153], v[174:177], v[52:55]
	v_mfma_f32_16x16x32_bf16 v[48:51], v[158:161], v[174:177], v[48:51]
	v_mfma_f32_16x16x32_bf16 v[36:39], v[150:153], v[182:185], v[36:39]
	v_mfma_f32_16x16x32_bf16 v[32:35], v[158:161], v[182:185], v[32:35]
	v_mfma_f32_16x16x32_bf16 v[20:23], v[150:153], v[192:195], v[20:23]
	v_mfma_f32_16x16x32_bf16 v[16:19], v[158:161], v[192:195], v[16:19]
	v_mfma_f32_16x16x32_bf16 v[60:63], v[154:157], v[170:173], v[60:63]
	v_mfma_f32_16x16x32_bf16 v[56:59], v[162:165], v[170:173], v[56:59]
	v_mfma_f32_16x16x32_bf16 v[52:55], v[154:157], v[178:181], v[52:55]
	v_mfma_f32_16x16x32_bf16 v[48:51], v[162:165], v[178:181], v[48:51]
	v_mfma_f32_16x16x32_bf16 v[36:39], v[154:157], v[186:189], v[36:39]
	v_mfma_f32_16x16x32_bf16 v[32:35], v[162:165], v[186:189], v[32:35]
	v_mfma_f32_16x16x32_bf16 v[20:23], v[154:157], v[196:199], v[20:23]
	v_mfma_f32_16x16x32_bf16 v[16:19], v[162:165], v[196:199], v[16:19]
	s_setprio 0
	s_barrier
	s_add_u32 s18, s18, 0x40080
	s_addc_u32 s19, s19, 0
	s_add_i32 s20, s20, s23
	v_lshl_add_u64 v[150:151], s[18:19], 0, v[130:131]
	s_mov_b32 m0, s20
	s_nop 0
	global_load_lds_dwordx4 v[150:151], off
	v_lshl_add_u64 v[150:151], s[18:19], 0, v[134:135]
	s_add_i32 m0, s20, 0x2000
	s_nop 0
	global_load_lds_dwordx4 v[150:151], off
	s_waitcnt vmcnt(6)
	s_barrier
	s_setprio 1
	v_mfma_f32_16x16x32_bf16 v[44:47], v[200:203], v[166:169], v[44:47]
	v_mfma_f32_16x16x32_bf16 v[40:43], v[208:211], v[166:169], v[40:43]
	v_mfma_f32_16x16x32_bf16 v[28:31], v[200:203], v[174:177], v[28:31]
	v_mfma_f32_16x16x32_bf16 v[24:27], v[208:211], v[174:177], v[24:27]
	v_mfma_f32_16x16x32_bf16 v[12:15], v[200:203], v[182:185], v[12:15]
	v_mfma_f32_16x16x32_bf16 v[8:11], v[208:211], v[182:185], v[8:11]
	v_mfma_f32_16x16x32_bf16 v[4:7], v[200:203], v[192:195], v[4:7]
	v_mfma_f32_16x16x32_bf16 v[0:3], v[208:211], v[192:195], v[0:3]
	v_mfma_f32_16x16x32_bf16 v[44:47], v[204:207], v[170:173], v[44:47]
	v_mfma_f32_16x16x32_bf16 v[40:43], v[214:217], v[170:173], v[40:43]
	v_mfma_f32_16x16x32_bf16 v[28:31], v[204:207], v[178:181], v[28:31]
	v_mfma_f32_16x16x32_bf16 v[24:27], v[214:217], v[178:181], v[24:27]
	v_mfma_f32_16x16x32_bf16 v[12:15], v[204:207], v[186:189], v[12:15]
	v_mfma_f32_16x16x32_bf16 v[8:11], v[214:217], v[186:189], v[8:11]
	v_mfma_f32_16x16x32_bf16 v[4:7], v[204:207], v[196:199], v[4:7]
	v_mfma_f32_16x16x32_bf16 v[0:3], v[214:217], v[196:199], v[0:3]
	s_setprio 0
	s_add_i32 s43, s43, 2
	s_add_u32 s16, s16, 0x100
	s_addc_u32 s17, s17, 0
	s_add_u32 s41, s41, 0x100
	s_addc_u32 s42, s42, 0
	s_cmp_gt_u32 s43, 13
	s_barrier

; #define PG8_STAGE(bufoff, gbase, voff) do { _Pragma("unroll") for (int _i = 0; _i < 2; ++_i) \
;         __builtin_amdgcn_global_load_lds((const unsigned*)((const char*)(gbase) + (voff)[_i]), (LAS unsigned*)(lds + (bufoff) + ldsw + _i * 8192), 16, 0, 0); } while (0)
; #define PG8_LDA(dst, b, h) do { _Pragma("unroll") for (int m = 0; m < 4; ++m) _Pragma("unroll") for (int k = 0; k < 2; ++k) dst[m][k] = *(const LAS bf16x8*)(lds + PG8_SA(b, h) + aoff + m * 2048 + k * 1024); } while (0)
; #define PG8_LDB(dst, b, h) do { _Pragma("unroll") for (int n = 0; n < 2; ++n) _Pragma("unroll") for (int k = 0; k < 2; ++k) dst[n][k] = *(const LAS bf16x8*)(lds + PG8_SB(b, h) + boff + n * 2048 + k * 1024); } while (0)
; #define PG8_MMA(ai, bj, At, Bt) do { __builtin_amdgcn_s_setprio(1); _Pragma("unroll") for (int m = 0; m < 4; ++m) _Pragma("unroll") for (int n = 0; n < 2; ++n) _Pragma("unroll") for (int k = 0; k < 2; ++k) \
;         acc[ai][bj][m][n] = __builtin_amdgcn_mfma_f32_16x16x32_bf16(Bt[n][k], At[m][k], acc[ai][bj][m][n], 0, 0, 0); __builtin_amdgcn_s_setprio(0); } while (0)
; #define PG8_WAIT_L(n) asm volatile("s_waitcnt lgkmcnt(" #n ")" ::: "memory")
; template <class Epi, bool AFTER = false>
; __device__ __forceinline__ void gemm_phase(LAS unsigned char* lds, const Gemm g, const StaticOrder& S, const Epi& E) {
;     ...
;         const bool has_next = S.next(ui + 1, nxt);
;         const char* nA = has_next ? (const char*)g.A + (size_t)nxt.pm * tstep : cA; const char* nB = has_next ? (const char*)g.Bt + (size_t)nxt.pn * tstep : cB;
;         for (int t = 0; t < nt; t += 2) {
;             const bool last = (t == nt - 2);
;             const char* a1 = cA + (size_t)(t + 1) * kstep;
;             const char* a2 = last ? nA : cA + (size_t)(t + 2) * kstep; const char* b2 = last ? nB : cB + (size_t)(t + 2) * kstep;
;             const char* a3 = a2 + kstep; const char* b3 = b2 + kstep;
;             PG8_LDB(B0, 0, 0); PG8_SCHED; PG8_LDA(At, 0, 0); PG8_STAGE(PG8_SA(1, 1), a1 + hstep, voffA);
;             PG8_WAIT_L(8); PG8_BAR; PG8_WAIT_L(0); PG8_MMA(0, 0, At, B0); PG8_BAR; PG8_SCHED;
;             PG8_LDB(B1, 0, 1); PG8_STAGE(PG8_SB(0, 0), b2, voffB);
;             PG8_BAR; PG8_WAIT_L(0); PG8_MMA(0, 1, At, B1); PG8_BAR;
;             PG8_LDA(At, 0, 1); PG8_STAGE(PG8_SA(0, 0), a2, voffA);
;             PG8_BAR; PG8_WAIT_L(0); PG8_MMA(1, 0, At, B0); PG8_BAR; PG8_SCHED;
.LBB0_419:
	s_ashr_i32 s17, s16, 31
	v_cmp_lt_i64_e32 vcc, s[18:19], v[144:145]
	s_lshl_b64 s[18:19], s[16:17], 19
	s_add_u32 s18, s74, s18
	s_addc_u32 s19, s75, s19
	s_and_b64 s[20:21], vcc, exec
	s_cselect_b32 s5, s19, s23
	s_cselect_b32 s7, s18, s22
	s_ashr_i32 s15, s14, 31
	s_lshl_b64 s[20:21], s[14:15], 19
	s_add_u32 s20, s40, s20
	s_addc_u32 s21, s41, s21
	s_and_b64 s[26:27], vcc, exec
	s_cselect_b32 s8, s21, s25
	s_cselect_b32 s15, s20, s24
	s_add_u32 s22, s22, 0x40080
	s_addc_u32 s23, s23, 0
	s_add_u32 s17, s24, 0x100
	s_addc_u32 s28, s25, 0
	s_mov_b32 s29, -2
	ds_read_b128 v[158:161], v151
	ds_read_b128 v[162:165], v151 offset:1024
	ds_read_b128 v[166:169], v151 offset:2048
	ds_read_b128 v[170:173], v151 offset:3072
	s_add_u32 s24, s22, 0xfffc0080
	s_addc_u32 s25, s23, -1
	s_cmp_eq_u32 s29, 12
	s_cselect_b32 s27, s5, s25
	s_cselect_b32 s26, s7, s24
	s_cselect_b32 s25, s8, s28
	s_cselect_b32 s24, s15, s17
	v_lshl_add_u64 v[148:149], s[22:23], 0, v[140:141]
	s_add_i32 m0, s43, 0xc000
	ds_read_b128 v[174:177], v152
	ds_read_b128 v[178:181], v152 offset:1024
	ds_read_b128 v[182:185], v152 offset:2048
	ds_read_b128 v[186:189], v152 offset:3072
	ds_read_b128 v[192:195], v152 offset:4096
	ds_read_b128 v[196:199], v152 offset:5120
	ds_read_b128 v[200:203], v152 offset:6144
	ds_read_b128 v[204:207], v152 offset:7168
	global_load_lds_dwordx4 v[148:149], off
	v_lshl_add_u64 v[148:149], s[22:23], 0, v[142:143]
	s_add_i32 m0, s43, 0xe000
	s_nop 0
	global_load_lds_dwordx4 v[148:149], off
	s_waitcnt lgkmcnt(8)
	s_barrier
	s_waitcnt lgkmcnt(0)
	s_setprio 1
	s_waitcnt lgkmcnt(0)
	v_mfma_f32_16x16x32_bf16 v[124:127], v[158:161], v[174:177], 0
	v_mfma_f32_16x16x32_bf16 v[120:123], v[166:169], v[174:177], 0
	v_mfma_f32_16x16x32_bf16 v[108:111], v[158:161], v[182:185], 0
	v_mfma_f32_16x16x32_bf16 v[104:107], v[166:169], v[182:185], 0
	v_mfma_f32_16x16x32_bf16 v[92:95], v[158:161], v[192:195], 0
	v_mfma_f32_16x16x32_bf16 v[88:91], v[166:169], v[192:195], 0
	v_mfma_f32_16x16x32_bf16 v[76:79], v[158:161], v[200:203], 0
	v_mfma_f32_16x16x32_bf16 v[72:75], v[166:169], v[200:203], 0
	v_mfma_f32_16x16x32_bf16 v[124:127], v[162:165], v[178:181], v[124:127]
	v_mfma_f32_16x16x32_bf16 v[120:123], v[170:173], v[178:181], v[120:123]
	v_mfma_f32_16x16x32_bf16 v[108:111], v[162:165], v[186:189], v[108:111]
	v_mfma_f32_16x16x32_bf16 v[104:107], v[170:173], v[186:189], v[104:107]
	v_mfma_f32_16x16x32_bf16 v[92:95], v[162:165], v[196:199], v[92:95]
	v_mfma_f32_16x16x32_bf16 v[88:91], v[170:173], v[196:199], v[88:91]
	v_mfma_f32_16x16x32_bf16 v[76:79], v[162:165], v[204:207], v[76:79]
	v_mfma_f32_16x16x32_bf16 v[72:75], v[170:173], v[204:207], v[72:75]
	s_setprio 0
	s_barrier
	s_add_i32 s30, s58, s42
	v_lshl_add_u64 v[148:149], s[24:25], 0, v[130:131]
	s_mov_b32 m0, s30
	ds_read_b128 v[208:211], v153
	ds_read_b128 v[214:217], v153 offset:1024
	ds_read_b128 v[218:221], v153 offset:2048
	ds_read_b128 v[222:225], v153 offset:3072
	global_load_lds_dwordx4 v[148:149], off
	v_lshl_add_u64 v[226:227], s[24:25], 0, v[134:135]
	s_add_i32 m0, s30, 0x2000
	s_nop 0
	global_load_lds_dwordx4 v[226:227], off
	s_barrier
	s_waitcnt lgkmcnt(0)
	s_setprio 1
	s_waitcnt lgkmcnt(0)
	v_mfma_f32_16x16x32_bf16 v[116:119], v[208:211], v[174:177], 0
	v_mfma_f32_16x16x32_bf16 v[112:115], v[218:221], v[174:177], 0
	v_mfma_f32_16x16x32_bf16 v[100:103], v[208:211], v[182:185], 0
	v_mfma_f32_16x16x32_bf16 v[96:99], v[218:221], v[182:185], 0
	v_mfma_f32_16x16x32_bf16 v[84:87], v[208:211], v[192:195], 0
	v_mfma_f32_16x16x32_bf16 v[80:83], v[218:221], v[192:195], 0
	v_mfma_f32_16x16x32_bf16 v[68:71], v[208:211], v[200:203], 0
	v_mfma_f32_16x16x32_bf16 v[64:67], v[218:221], v[200:203], 0
	v_mfma_f32_16x16x32_bf16 v[116:119], v[214:217], v[178:181], v[116:119]
	v_mfma_f32_16x16x32_bf16 v[112:115], v[222:225], v[178:181], v[112:115]
	v_mfma_f32_16x16x32_bf16 v[100:103], v[214:217], v[186:189], v[100:103]
	v_mfma_f32_16x16x32_bf16 v[96:99], v[222:225], v[186:189], v[96:99]
	v_mfma_f32_16x16x32_bf16 v[84:87], v[214:217], v[196:199], v[84:87]
	v_mfma_f32_16x16x32_bf16 v[80:83], v[222:225], v[196:199], v[80:83]
	v_mfma_f32_16x16x32_bf16 v[68:71], v[214:217], v[204:207], v[68:71]
	v_mfma_f32_16x16x32_bf16 v[64:67], v[222:225], v[204:207], v[64:67]
	s_setprio 0
	s_mov_b32 m0, s43
	v_lshl_add_u64 v[228:229], s[26:27], 0, v[128:129]
	s_barrier
	ds_read_b128 v[174:177], v152 offset:16384
	ds_read_b128 v[178:181], v152 offset:17408
	ds_read_b128 v[182:185], v152 offset:18432
	ds_read_b128 v[186:189], v152 offset:19456
	ds_read_b128 v[192:195], v152 offset:20480
	ds_read_b128 v[196:199], v152 offset:21504
	ds_read_b128 v[200:203], v152 offset:22528
	ds_read_b128 v[204:207], v152 offset:23552
	global_load_lds_dwordx4 v[228:229], off
	v_lshl_add_u64 v[230:231], s[26:27], 0, v[132:133]
	s_mov_b32 m0, s44
	s_nop 0
	global_load_lds_dwordx4 v[230:231], off
	s_barrier
	s_waitcnt lgkmcnt(0)
	s_setprio 1
	s_waitcnt lgkmcnt(0)
	v_mfma_f32_16x16x32_bf16 v[60:63], v[158:161], v[174:177], 0
	v_mfma_f32_16x16x32_bf16 v[56:59], v[166:169], v[174:177], 0
	v_mfma_f32_16x16x32_bf16 v[44:47], v[158:161], v[182:185], 0
	v_mfma_f32_16x16x32_bf16 v[40:43], v[166:169], v[182:185], 0
	v_mfma_f32_16x16x32_bf16 v[28:31], v[158:161], v[192:195], 0
	v_mfma_f32_16x16x32_bf16 v[24:27], v[166:169], v[192:195], 0
	v_mfma_f32_16x16x32_bf16 v[12:15], v[158:161], v[200:203], 0
	v_mfma_f32_16x16x32_bf16 v[8:11], v[166:169], v[200:203], 0
	v_mfma_f32_16x16x32_bf16 v[60:63], v[162:165], v[178:181], v[60:63]
	v_mfma_f32_16x16x32_bf16 v[56:59], v[170:173], v[178:181], v[56:59]
	v_mfma_f32_16x16x32_bf16 v[44:47], v[162:165], v[186:189], v[44:47]
	v_mfma_f32_16x16x32_bf16 v[40:43], v[170:173], v[186:189], v[40:43]
	v_mfma_f32_16x16x32_bf16 v[28:31], v[162:165], v[196:199], v[28:31]
	v_mfma_f32_16x16x32_bf16 v[24:27], v[170:173], v[196:199], v[24:27]
	v_mfma_f32_16x16x32_bf16 v[12:15], v[162:165], v[204:207], v[12:15]
	v_mfma_f32_16x16x32_bf16 v[8:11], v[170:173], v[204:207], v[8:11]
	s_setprio 0
	s_barrier
; #define PG8_STAGE(bufoff, gbase, voff) do { _Pragma("unroll") for (int _i = 0; _i < 2; ++_i) \
;         __builtin_amdgcn_global_load_lds((const unsigned*)((const char*)(gbase) + (voff)[_i]), (LAS unsigned*)(lds + (bufoff) + ldsw + _i * 8192), 16, 0, 0); } while (0)
; #define PG8_LDA(dst, b, h) do { _Pragma("unroll") for (int m = 0; m < 4; ++m) _Pragma("unroll") for (int k = 0; k < 2; ++k) dst[m][k] = *(const LAS bf16x8*)(lds + PG8_SA(b, h) + aoff + m * 2048 + k * 1024); } while (0)
; #define PG8_LDB(dst, b, h) do { _Pragma("unroll") for (int n = 0; n < 2; ++n) _Pragma("unroll") for (int k = 0; k < 2; ++k) dst[n][k] = *(const LAS bf16x8*)(lds + PG8_SB(b, h) + boff + n * 2048 + k * 1024); } while (0)
; #define PG8_MMA(ai, bj, At, Bt) do { __builtin_amdgcn_s_setprio(1); _Pragma("unroll") for (int m = 0; m < 4; ++m) _Pragma("unroll") for (int n = 0; n < 2; ++n) _Pragma("unroll") for (int k = 0; k < 2; ++k) \
;         acc[ai][bj][m][n] = __builtin_amdgcn_mfma_f32_16x16x32_bf16(Bt[n][k], At[m][k], acc[ai][bj][m][n], 0, 0, 0); __builtin_amdgcn_s_setprio(0); } while (0)
; #define PG8_WAIT_V(n) asm volatile("s_waitcnt vmcnt(" #n ")" ::: "memory")
; #define PG8_WAIT_L(n) asm volatile("s_waitcnt lgkmcnt(" #n ")" ::: "memory")
; #define PG8_BAR __builtin_amdgcn_s_barrier()
; #define PG8_SCHED __builtin_amdgcn_sched_barrier(0)
; #define PG8_LDA(dst, b, h) do { _Pragma("unroll") for (int m = 0; m < 4; ++m) _Pragma("unroll") for (int k = 0; k < 2; ++k) dst[m][k] = *(const LAS bf16x8*)(lds + PG8_SA(b, h) + aoff + m * 2048 + k * 1024); } while (0)
; #define PG8_LDB(dst, b, h) do { _Pragma("unroll") for (int n = 0; n < 2; ++n) _Pragma("unroll") for (int k = 0; k < 2; ++k) dst[n][k] = *(const LAS bf16x8*)(lds + PG8_SB(b, h) + boff + n * 2048 + k * 1024); } while (0)
; #define PG8_BAR __builtin_amdgcn_s_barrier()
; template <class Epi, bool AFTER = false>
; __device__ __forceinline__ void gemm_phase(LAS unsigned char* lds, const Gemm g, const StaticOrder& S, const Epi& E) {
;     ...
;             PG8_STAGE(PG8_SB(0, 1), b2 + hstep, voffB);
;             PG8_WAIT_V(6); PG8_BAR; PG8_MMA(1, 1, At, B1); PG8_BAR;
;             PG8_LDB(B0, 1, 0); PG8_SCHED; PG8_LDA(At, 1, 0); PG8_STAGE(PG8_SA(0, 1), a2 + hstep, voffA);
;             PG8_WAIT_L(8); PG8_BAR; PG8_WAIT_L(0); PG8_MMA(0, 0, At, B0); PG8_BAR; PG8_SCHED;
;             PG8_LDB(B1, 1, 1); PG8_STAGE(PG8_SB(1, 0), b3, voffB);
	s_add_u32 s30, s24, 0x40000
	s_addc_u32 s31, s25, 0
	s_add_i32 s34, s59, s42
	v_lshl_add_u64 v[158:159], s[30:31], 0, v[130:131]
	s_mov_b32 m0, s34
	s_nop 0
	global_load_lds_dwordx4 v[158:159], off
	v_lshl_add_u64 v[158:159], s[30:31], 0, v[134:135]
	s_add_i32 m0, s34, 0x2000
	s_nop 0
	global_load_lds_dwordx4 v[158:159], off
	s_waitcnt vmcnt(6)
	s_barrier
	s_setprio 1
	v_mfma_f32_16x16x32_bf16 v[52:55], v[208:211], v[174:177], 0
	v_mfma_f32_16x16x32_bf16 v[48:51], v[218:221], v[174:177], 0
	v_mfma_f32_16x16x32_bf16 v[36:39], v[208:211], v[182:185], 0
	v_mfma_f32_16x16x32_bf16 v[32:35], v[218:221], v[182:185], 0
	v_mfma_f32_16x16x32_bf16 v[20:23], v[208:211], v[192:195], 0
	v_mfma_f32_16x16x32_bf16 v[16:19], v[218:221], v[192:195], 0
	v_mfma_f32_16x16x32_bf16 v[4:7], v[208:211], v[200:203], 0
	v_mfma_f32_16x16x32_bf16 v[0:3], v[218:221], v[200:203], 0
	v_mfma_f32_16x16x32_bf16 v[52:55], v[214:217], v[178:181], v[52:55]
	v_mfma_f32_16x16x32_bf16 v[48:51], v[222:225], v[178:181], v[48:51]
	v_mfma_f32_16x16x32_bf16 v[36:39], v[214:217], v[186:189], v[36:39]
	v_mfma_f32_16x16x32_bf16 v[32:35], v[222:225], v[186:189], v[32:35]
	v_mfma_f32_16x16x32_bf16 v[20:23], v[214:217], v[196:199], v[20:23]
	v_mfma_f32_16x16x32_bf16 v[16:19], v[222:225], v[196:199], v[16:19]
	v_mfma_f32_16x16x32_bf16 v[4:7], v[214:217], v[204:207], v[4:7]
	v_mfma_f32_16x16x32_bf16 v[0:3], v[222:225], v[204:207], v[0:3]
	s_setprio 0
	s_add_i32 s30, 0, 0x18000
	v_add_u32_e32 v136, s30, v150
	s_barrier
	ds_read_b128 v[158:161], v136
	ds_read_b128 v[162:165], v136 offset:1024
	ds_read_b128 v[166:169], v136 offset:2048
	ds_read_b128 v[170:173], v136 offset:3072
	s_add_u32 s26, s26, 0x40000
	s_addc_u32 s27, s27, 0
	s_mov_b32 m0, s45
	v_lshl_add_u64 v[208:209], s[26:27], 0, v[128:129]
	ds_read_b128 v[174:177], v152 offset:32768
	ds_read_b128 v[178:181], v152 offset:33792
	ds_read_b128 v[182:185], v152 offset:34816
	ds_read_b128 v[186:189], v152 offset:35840
	ds_read_b128 v[192:195], v152 offset:36864
	ds_read_b128 v[196:199], v152 offset:37888
	ds_read_b128 v[200:203], v152 offset:38912
	ds_read_b128 v[204:207], v152 offset:39936
	global_load_lds_dwordx4 v[208:209], off
	v_lshl_add_u64 v[208:209], s[26:27], 0, v[132:133]
	s_mov_b32 m0, s46
	s_nop 0
	global_load_lds_dwordx4 v[208:209], off
	s_waitcnt lgkmcnt(8)
	s_barrier
	s_waitcnt lgkmcnt(0)
	s_setprio 1
	s_waitcnt lgkmcnt(0)
	v_mfma_f32_16x16x32_bf16 v[124:127], v[158:161], v[174:177], v[124:127]
	v_mfma_f32_16x16x32_bf16 v[120:123], v[166:169], v[174:177], v[120:123]
	v_mfma_f32_16x16x32_bf16 v[108:111], v[158:161], v[182:185], v[108:111]
	v_mfma_f32_16x16x32_bf16 v[104:107], v[166:169], v[182:185], v[104:107]
	v_mfma_f32_16x16x32_bf16 v[92:95], v[158:161], v[192:195], v[92:95]
	v_mfma_f32_16x16x32_bf16 v[88:91], v[166:169], v[192:195], v[88:91]
	v_mfma_f32_16x16x32_bf16 v[76:79], v[158:161], v[200:203], v[76:79]
	v_mfma_f32_16x16x32_bf16 v[72:75], v[166:169], v[200:203], v[72:75]
	v_mfma_f32_16x16x32_bf16 v[124:127], v[162:165], v[178:181], v[124:127]
	v_mfma_f32_16x16x32_bf16 v[120:123], v[170:173], v[178:181], v[120:123]
	v_mfma_f32_16x16x32_bf16 v[108:111], v[162:165], v[186:189], v[108:111]
	v_mfma_f32_16x16x32_bf16 v[104:107], v[170:173], v[186:189], v[104:107]
	v_mfma_f32_16x16x32_bf16 v[92:95], v[162:165], v[196:199], v[92:95]
	v_mfma_f32_16x16x32_bf16 v[88:91], v[170:173], v[196:199], v[88:91]
	v_mfma_f32_16x16x32_bf16 v[76:79], v[162:165], v[204:207], v[76:79]
	v_mfma_f32_16x16x32_bf16 v[72:75], v[170:173], v[204:207], v[72:75]
	s_setprio 0
	s_barrier
	s_add_i32 s26, 0, 0x1c000
	s_add_i32 s27, s30, s42
	v_add_u32_e32 v136, s26, v150
	v_lshl_add_u64 v[148:149], v[148:149], 0, s[10:11]
	s_mov_b32 m0, s27
	ds_read_b128 v[208:211], v136
	ds_read_b128 v[214:217], v136 offset:1024
	ds_read_b128 v[218:221], v136 offset:2048
	ds_read_b128 v[222:225], v136 offset:3072
	global_load_lds_dwordx4 v[148:149], off
	v_lshl_add_u64 v[148:149], v[226:227], 0, s[10:11]
	s_add_i32 m0, s27, 0x2000
	s_nop 0
	global_load_lds_dwordx4 v[148:149], off
	s_barrier
; #define PG8_STAGE(bufoff, gbase, voff) do { _Pragma("unroll") for (int _i = 0; _i < 2; ++_i) \
;         __builtin_amdgcn_global_load_lds((const unsigned*)((const char*)(gbase) + (voff)[_i]), (LAS unsigned*)(lds + (bufoff) + ldsw + _i * 8192), 16, 0, 0); } while (0)
; #define PG8_LDA(dst, b, h) do { _Pragma("unroll") for (int m = 0; m < 4; ++m) _Pragma("unroll") for (int k = 0; k < 2; ++k) dst[m][k] = *(const LAS bf16x8*)(lds + PG8_SA(b, h) + aoff + m * 2048 + k * 1024); } while (0)
; #define PG8_MMA(ai, bj, At, Bt) do { __builtin_amdgcn_s_setprio(1); _Pragma("unroll") for (int m = 0; m < 4; ++m) _Pragma("unroll") for (int n = 0; n < 2; ++n) _Pragma("unroll") for (int k = 0; k < 2; ++k) \
;         acc[ai][bj][m][n] = __builtin_amdgcn_mfma_f32_16x16x32_bf16(Bt[n][k], At[m][k], acc[ai][bj][m][n], 0, 0, 0); __builtin_amdgcn_s_setprio(0); } while (0)
; #define PG8_WAIT_V(n) asm volatile("s_waitcnt vmcnt(" #n ")" ::: "memory")
; #define PG8_WAIT_L(n) asm volatile("s_waitcnt lgkmcnt(" #n ")" ::: "memory")
; #define PG8_BAR __builtin_amdgcn_s_barrier()
; #define PG8_SCHED __builtin_amdgcn_sched_barrier(0)
; #define PG8_LDA(dst, b, h) do { _Pragma("unroll") for (int m = 0; m < 4; ++m) _Pragma("unroll") for (int k = 0; k < 2; ++k) dst[m][k] = *(const LAS bf16x8*)(lds + PG8_SA(b, h) + aoff + m * 2048 + k * 1024); } while (0)
; #define PG8_MMA(ai, bj, At, Bt) do { __builtin_amdgcn_s_setprio(1); _Pragma("unroll") for (int m = 0; m < 4; ++m) _Pragma("unroll") for (int n = 0; n < 2; ++n) _Pragma("unroll") for (int k = 0; k < 2; ++k) \
;         acc[ai][bj][m][n] = __builtin_amdgcn_mfma_f32_16x16x32_bf16(Bt[n][k], At[m][k], acc[ai][bj][m][n], 0, 0, 0); __builtin_amdgcn_s_setprio(0); } while (0)
; #define PG8_WAIT_V(n) asm volatile("s_waitcnt vmcnt(" #n ")" ::: "memory")
; #define PG8_WAIT_L(n) asm volatile("s_waitcnt lgkmcnt(" #n ")" ::: "memory")
; template <class Epi, bool AFTER = false>
; __device__ __forceinline__ void gemm_phase(LAS unsigned char* lds, const Gemm g, const StaticOrder& S, const Epi& E) {
;     ...
;             PG8_BAR; PG8_WAIT_L(0); PG8_MMA(0, 1, At, B1); PG8_BAR;
;             PG8_LDA(At, 1, 1); PG8_STAGE(PG8_SA(1, 0), a3, voffA);
;             PG8_BAR; PG8_WAIT_L(0); PG8_MMA(1, 0, At, B0); PG8_BAR; PG8_SCHED;
;             PG8_STAGE(PG8_SB(1, 1), b3 + hstep, voffB);
;             PG8_WAIT_V(6); PG8_BAR; PG8_MMA(1, 1, At, B1); PG8_BAR;
;         }
	s_waitcnt lgkmcnt(0)
	s_setprio 1
	s_waitcnt lgkmcnt(0)
	v_mfma_f32_16x16x32_bf16 v[116:119], v[208:211], v[174:177], v[116:119]
	v_mfma_f32_16x16x32_bf16 v[112:115], v[218:221], v[174:177], v[112:115]
	v_mfma_f32_16x16x32_bf16 v[100:103], v[208:211], v[182:185], v[100:103]
	v_mfma_f32_16x16x32_bf16 v[96:99], v[218:221], v[182:185], v[96:99]
	v_mfma_f32_16x16x32_bf16 v[84:87], v[208:211], v[192:195], v[84:87]
	v_mfma_f32_16x16x32_bf16 v[80:83], v[218:221], v[192:195], v[80:83]
	v_mfma_f32_16x16x32_bf16 v[68:71], v[208:211], v[200:203], v[68:71]
	v_mfma_f32_16x16x32_bf16 v[64:67], v[218:221], v[200:203], v[64:67]
	v_mfma_f32_16x16x32_bf16 v[116:119], v[214:217], v[178:181], v[116:119]
	v_mfma_f32_16x16x32_bf16 v[112:115], v[222:225], v[178:181], v[112:115]
	v_mfma_f32_16x16x32_bf16 v[100:103], v[214:217], v[186:189], v[100:103]
	v_mfma_f32_16x16x32_bf16 v[96:99], v[222:225], v[186:189], v[96:99]
	v_mfma_f32_16x16x32_bf16 v[84:87], v[214:217], v[196:199], v[84:87]
	v_mfma_f32_16x16x32_bf16 v[80:83], v[222:225], v[196:199], v[80:83]
	v_mfma_f32_16x16x32_bf16 v[68:71], v[214:217], v[204:207], v[68:71]
	v_mfma_f32_16x16x32_bf16 v[64:67], v[222:225], v[204:207], v[64:67]
	s_setprio 0
	s_mov_b32 m0, s54
	v_lshl_add_u64 v[148:149], v[228:229], 0, s[10:11]
	s_barrier
	ds_read_b128 v[174:177], v152 offset:49152
	ds_read_b128 v[178:181], v152 offset:50176
	ds_read_b128 v[182:185], v152 offset:51200
	ds_read_b128 v[186:189], v152 offset:52224
	ds_read_b128 v[192:195], v152 offset:53248
	ds_read_b128 v[196:199], v152 offset:54272
	ds_read_b128 v[200:203], v152 offset:55296
	ds_read_b128 v[204:207], v152 offset:56320
	global_load_lds_dwordx4 v[148:149], off
	v_lshl_add_u64 v[148:149], v[230:231], 0, s[10:11]
	s_mov_b32 m0, s55
	s_nop 0
	global_load_lds_dwordx4 v[148:149], off
	s_barrier
	s_waitcnt lgkmcnt(0)
	s_setprio 1
	s_waitcnt lgkmcnt(0)
	v_mfma_f32_16x16x32_bf16 v[60:63], v[158:161], v[174:177], v[60:63]
	v_mfma_f32_16x16x32_bf16 v[56:59], v[166:169], v[174:177], v[56:59]
	v_mfma_f32_16x16x32_bf16 v[44:47], v[158:161], v[182:185], v[44:47]
	v_mfma_f32_16x16x32_bf16 v[40:43], v[166:169], v[182:185], v[40:43]
	v_mfma_f32_16x16x32_bf16 v[28:31], v[158:161], v[192:195], v[28:31]
	v_mfma_f32_16x16x32_bf16 v[24:27], v[166:169], v[192:195], v[24:27]
	v_mfma_f32_16x16x32_bf16 v[12:15], v[158:161], v[200:203], v[12:15]
	v_mfma_f32_16x16x32_bf16 v[8:11], v[166:169], v[200:203], v[8:11]
	v_mfma_f32_16x16x32_bf16 v[60:63], v[162:165], v[178:181], v[60:63]
	v_mfma_f32_16x16x32_bf16 v[56:59], v[170:173], v[178:181], v[56:59]
	v_mfma_f32_16x16x32_bf16 v[44:47], v[162:165], v[186:189], v[44:47]
	v_mfma_f32_16x16x32_bf16 v[40:43], v[170:173], v[186:189], v[40:43]
	v_mfma_f32_16x16x32_bf16 v[28:31], v[162:165], v[196:199], v[28:31]
	v_mfma_f32_16x16x32_bf16 v[24:27], v[170:173], v[196:199], v[24:27]
	v_mfma_f32_16x16x32_bf16 v[12:15], v[162:165], v[204:207], v[12:15]
	v_mfma_f32_16x16x32_bf16 v[8:11], v[170:173], v[204:207], v[8:11]
	s_setprio 0
	s_barrier
	s_add_u32 s24, s24, 0x40080
	s_addc_u32 s25, s25, 0
	s_add_i32 s26, s26, s42
	v_lshl_add_u64 v[148:149], s[24:25], 0, v[130:131]
	s_mov_b32 m0, s26
	s_nop 0
	global_load_lds_dwordx4 v[148:149], off
	v_lshl_add_u64 v[148:149], s[24:25], 0, v[134:135]
	s_add_i32 m0, s26, 0x2000
	s_nop 0
	global_load_lds_dwordx4 v[148:149], off
	s_waitcnt vmcnt(6)
	s_barrier
	s_setprio 1
	v_mfma_f32_16x16x32_bf16 v[52:55], v[208:211], v[174:177], v[52:55]
	v_mfma_f32_16x16x32_bf16 v[48:51], v[218:221], v[174:177], v[48:51]
	v_mfma_f32_16x16x32_bf16 v[36:39], v[208:211], v[182:185], v[36:39]
	v_mfma_f32_16x16x32_bf16 v[32:35], v[218:221], v[182:185], v[32:35]
	v_mfma_f32_16x16x32_bf16 v[20:23], v[208:211], v[192:195], v[20:23]
	v_mfma_f32_16x16x32_bf16 v[16:19], v[218:221], v[192:195], v[16:19]
	v_mfma_f32_16x16x32_bf16 v[4:7], v[208:211], v[200:203], v[4:7]
	v_mfma_f32_16x16x32_bf16 v[0:3], v[218:221], v[200:203], v[0:3]
	v_mfma_f32_16x16x32_bf16 v[52:55], v[214:217], v[178:181], v[52:55]
	v_mfma_f32_16x16x32_bf16 v[48:51], v[222:225], v[178:181], v[48:51]
	v_mfma_f32_16x16x32_bf16 v[36:39], v[214:217], v[186:189], v[36:39]
	v_mfma_f32_16x16x32_bf16 v[32:35], v[222:225], v[186:189], v[32:35]
	v_mfma_f32_16x16x32_bf16 v[20:23], v[214:217], v[196:199], v[20:23]
	v_mfma_f32_16x16x32_bf16 v[16:19], v[222:225], v[196:199], v[16:19]
	v_mfma_f32_16x16x32_bf16 v[4:7], v[214:217], v[204:207], v[4:7]
	v_mfma_f32_16x16x32_bf16 v[0:3], v[222:225], v[204:207], v[0:3]
	s_setprio 0
	s_add_i32 s29, s29, 2
	s_add_u32 s22, s22, 0x100
	s_addc_u32 s23, s23, 0
	s_add_u32 s17, s17, 0x100
	s_addc_u32 s28, s28, 0
	s_cmp_gt_u32 s29, 13
	s_barrier
